# W_out GEMM mid-tile rescale: 16 row-statistic loads issued together up front with counted vmcnt
# baseline (speedup 1.0000x reference)
.LBB0_867:
	v_mov_b32_e32 v80, v192
	s_mov_b32 s36, 0x358637bd
	v_and_b32_e32 v82, 15, v80
	v_ashrrev_i32_e32 v80, 2, v80
	v_and_b32_e32 v80, 0xffffffc0, v80
	v_add3_u32 v132, v82, s30, v80
	v_ashrrev_i32_e32 v133, 31, v132
	v_lshl_add_u64 v[82:83], v[132:133], 2, s[90:91]
	v_add_co_u32_e32 v134, vcc, 0xc0000, v82
	s_mov_b64 s[46:47], s[60:61]
	s_nop 0
	v_addc_co_u32_e32 v135, vcc, 0, v83, vcc
	v_add_co_u32_e32 v82, vcc, 0xe0000, v82
	s_nop 0
	s_nop 0
	v_addc_co_u32_e32 v83, vcc, 0, v83, vcc
	global_load_dword v204, v[134:135], off
	global_load_dword v205, v[82:83], off
	global_load_dword v206, v[134:135], off offset:64
	global_load_dword v207, v[82:83], off offset:64
	global_load_dword v208, v[134:135], off offset:128
	global_load_dword v209, v[82:83], off offset:128
	global_load_dword v210, v[134:135], off offset:192
	global_load_dword v211, v[82:83], off offset:192
	global_load_dword v212, v[134:135], off offset:512
	global_load_dword v213, v[82:83], off offset:512
	global_load_dword v214, v[134:135], off offset:576
	global_load_dword v215, v[82:83], off offset:576
	global_load_dword v216, v[134:135], off offset:640
	global_load_dword v217, v[82:83], off offset:640
	global_load_dword v218, v[134:135], off offset:704
	global_load_dword v219, v[82:83], off offset:704
	v_mov_b64_e32 v[82:83], s[36:37]
	s_mov_b64 s[44:45], s[76:77]
	s_waitcnt vmcnt(14)
	v_pk_fma_f32 v[134:135], v[204:205], s[70:71], v[82:83] op_sel_hi:[1,0,0]
	s_nop 0
	v_mul_f32_e32 v80, 0x4b800000, v134
	v_cmp_gt_f32_e64 s[40:41], s19, v134
	v_cmp_gt_f32_e32 vcc, s19, v135
	s_nop 0
	v_cndmask_b32_e64 v80, v134, v80, s[40:41]
	v_rsq_f32_e32 v134, v80
	v_mul_f32_e32 v80, 0x4b800000, v135
	v_cndmask_b32_e32 v80, v135, v80, vcc
	v_rsq_f32_e32 v135, v80
	s_nop 0
	v_pk_mul_f32 v[136:137], v[134:135], s[8:9] op_sel_hi:[1,0]
	s_nop 0
	v_cndmask_b32_e64 v80, v134, v136, s[40:41]
	v_cndmask_b32_e32 v133, v135, v137, vcc
	v_div_scale_f32 v134, s[36:37], v133, v133, v80
	v_rcp_f32_e32 v135, v134
	s_nop 0
	v_fma_f32 v136, -v134, v135, 1.0
	v_fmac_f32_e32 v135, v136, v135
	v_div_scale_f32 v136, vcc, v80, v133, v80
	v_mul_f32_e32 v137, v136, v135
	v_fma_f32 v138, -v134, v137, v136
	v_fmac_f32_e32 v137, v138, v135
	v_fma_f32 v134, -v134, v137, v136
	v_div_fmas_f32 v134, v134, v135, v137
	v_div_fixup_f32 v80, v134, v133, v80
	v_add_u32_e32 v134, 16, v132
	v_ashrrev_i32_e32 v135, 31, v134
	v_lshl_add_u64 v[134:135], v[134:135], 2, s[90:91]
	v_add_co_u32_e32 v136, vcc, s18, v134
	v_pk_mul_f32 v[130:131], v[80:81], v[130:131] op_sel_hi:[0,1]
	s_nop 0
	v_addc_co_u32_e32 v137, vcc, 0, v135, vcc
	v_add_co_u32_e32 v134, vcc, s31, v134
	s_nop 0
	s_nop 0
	v_addc_co_u32_e32 v135, vcc, 0, v135, vcc
	s_nop 0
	v_pk_mul_f32 v[128:129], v[80:81], v[128:129] op_sel_hi:[0,1]
	v_pk_mul_f32 v[126:127], v[80:81], v[126:127] op_sel_hi:[0,1]
	v_pk_mul_f32 v[124:125], v[80:81], v[124:125] op_sel_hi:[0,1]
	v_pk_mul_f32 v[122:123], v[80:81], v[122:123] op_sel_hi:[0,1]
	v_pk_mul_f32 v[120:121], v[80:81], v[120:121] op_sel_hi:[0,1]
	v_pk_mul_f32 v[118:119], v[80:81], v[118:119] op_sel_hi:[0,1]
	v_pk_mul_f32 v[116:117], v[80:81], v[116:117] op_sel_hi:[0,1]
	s_waitcnt vmcnt(12)
	v_pk_fma_f32 v[134:135], v[206:207], s[70:71], v[82:83] op_sel_hi:[1,0,0]
	s_nop 0
	v_mul_f32_e32 v80, 0x4b800000, v134
	v_cmp_gt_f32_e64 s[40:41], s19, v134
	v_cmp_gt_f32_e32 vcc, s19, v135
	s_nop 0
	v_cndmask_b32_e64 v80, v134, v80, s[40:41]
	v_rsq_f32_e32 v134, v80
	v_mul_f32_e32 v80, 0x4b800000, v135
	v_cndmask_b32_e32 v80, v135, v80, vcc
	v_rsq_f32_e32 v135, v80
	s_nop 0
	v_pk_mul_f32 v[136:137], v[134:135], s[8:9] op_sel_hi:[1,0]
	s_nop 0
	v_cndmask_b32_e64 v80, v134, v136, s[40:41]
	v_cndmask_b32_e32 v133, v135, v137, vcc
	v_div_scale_f32 v134, s[36:37], v133, v133, v80
	v_rcp_f32_e32 v135, v134
	s_nop 0
	v_fma_f32 v136, -v134, v135, 1.0
	v_fmac_f32_e32 v135, v136, v135
	v_div_scale_f32 v136, vcc, v80, v133, v80
	v_mul_f32_e32 v137, v136, v135
	v_fma_f32 v138, -v134, v137, v136
	v_fmac_f32_e32 v137, v138, v135
	v_fma_f32 v134, -v134, v137, v136
	v_div_fmas_f32 v134, v134, v135, v137
	v_div_fixup_f32 v80, v134, v133, v80
	v_add_u32_e32 v134, 32, v132
	v_ashrrev_i32_e32 v135, 31, v134
	v_lshl_add_u64 v[134:135], v[134:135], 2, s[90:91]
	v_add_co_u32_e32 v136, vcc, s18, v134
	v_pk_mul_f32 v[114:115], v[80:81], v[114:115] op_sel_hi:[0,1]
	s_nop 0
	v_addc_co_u32_e32 v137, vcc, 0, v135, vcc
	v_add_co_u32_e32 v134, vcc, s31, v134
	s_nop 0
	s_nop 0
	v_addc_co_u32_e32 v135, vcc, 0, v135, vcc
	s_nop 0
	v_pk_mul_f32 v[112:113], v[80:81], v[112:113] op_sel_hi:[0,1]
	v_pk_mul_f32 v[110:111], v[80:81], v[110:111] op_sel_hi:[0,1]
	v_pk_mul_f32 v[108:109], v[80:81], v[108:109] op_sel_hi:[0,1]
	v_pk_mul_f32 v[106:107], v[80:81], v[106:107] op_sel_hi:[0,1]
	v_pk_mul_f32 v[104:105], v[80:81], v[104:105] op_sel_hi:[0,1]
	v_pk_mul_f32 v[102:103], v[80:81], v[102:103] op_sel_hi:[0,1]
	v_pk_mul_f32 v[100:101], v[80:81], v[100:101] op_sel_hi:[0,1]
	s_waitcnt vmcnt(10)
	v_pk_fma_f32 v[134:135], v[208:209], s[70:71], v[82:83] op_sel_hi:[1,0,0]
	s_nop 0
	v_mul_f32_e32 v80, 0x4b800000, v134
	v_cmp_gt_f32_e64 s[40:41], s19, v134
	v_cmp_gt_f32_e32 vcc, s19, v135
	s_nop 0
	v_cndmask_b32_e64 v80, v134, v80, s[40:41]
	v_rsq_f32_e32 v134, v80
	v_mul_f32_e32 v80, 0x4b800000, v135
	v_cndmask_b32_e32 v80, v135, v80, vcc
	v_rsq_f32_e32 v135, v80
	s_nop 0
	v_pk_mul_f32 v[136:137], v[134:135], s[8:9] op_sel_hi:[1,0]
	s_nop 0
	v_cndmask_b32_e64 v80, v134, v136, s[40:41]
	v_cndmask_b32_e32 v133, v135, v137, vcc
	v_div_scale_f32 v134, s[36:37], v133, v133, v80
	v_rcp_f32_e32 v135, v134
	s_nop 0
	v_fma_f32 v136, -v134, v135, 1.0
	v_fmac_f32_e32 v135, v136, v135
	v_div_scale_f32 v136, vcc, v80, v133, v80
	v_mul_f32_e32 v137, v136, v135
	v_fma_f32 v138, -v134, v137, v136
	v_fmac_f32_e32 v137, v138, v135
	v_fma_f32 v134, -v134, v137, v136
	v_div_fmas_f32 v134, v134, v135, v137
	v_div_fixup_f32 v80, v134, v133, v80
	v_add_u32_e32 v134, 48, v132
	v_ashrrev_i32_e32 v135, 31, v134
	v_lshl_add_u64 v[134:135], v[134:135], 2, s[90:91]
	v_add_co_u32_e32 v136, vcc, s18, v134
	v_pk_mul_f32 v[98:99], v[80:81], v[98:99] op_sel_hi:[0,1]
	s_nop 0
	v_addc_co_u32_e32 v137, vcc, 0, v135, vcc
	v_add_co_u32_e32 v134, vcc, s31, v134
	s_nop 0
	s_nop 0
	v_addc_co_u32_e32 v135, vcc, 0, v135, vcc
	s_nop 0
	v_pk_mul_f32 v[96:97], v[80:81], v[96:97] op_sel_hi:[0,1]
	v_pk_mul_f32 v[94:95], v[80:81], v[94:95] op_sel_hi:[0,1]
	v_pk_mul_f32 v[92:93], v[80:81], v[92:93] op_sel_hi:[0,1]
	v_pk_mul_f32 v[90:91], v[80:81], v[90:91] op_sel_hi:[0,1]
	v_pk_mul_f32 v[88:89], v[80:81], v[88:89] op_sel_hi:[0,1]
	v_pk_mul_f32 v[86:87], v[80:81], v[86:87] op_sel_hi:[0,1]
	v_pk_mul_f32 v[84:85], v[80:81], v[84:85] op_sel_hi:[0,1]
	s_waitcnt vmcnt(8)
	v_pk_fma_f32 v[134:135], v[210:211], s[70:71], v[82:83] op_sel_hi:[1,0,0]
	s_nop 0
	v_mul_f32_e32 v80, 0x4b800000, v134
	v_cmp_gt_f32_e64 s[40:41], s19, v134
	v_cmp_gt_f32_e32 vcc, s19, v135
	s_nop 0
	v_cndmask_b32_e64 v80, v134, v80, s[40:41]
	v_rsq_f32_e32 v134, v80
	v_mul_f32_e32 v80, 0x4b800000, v135
	v_cndmask_b32_e32 v80, v135, v80, vcc
	v_rsq_f32_e32 v135, v80
	s_nop 0
	v_pk_mul_f32 v[136:137], v[134:135], s[8:9] op_sel_hi:[1,0]
	s_nop 0
	v_cndmask_b32_e64 v80, v134, v136, s[40:41]
	v_cndmask_b32_e32 v133, v135, v137, vcc
	v_div_scale_f32 v134, s[36:37], v133, v133, v80
	v_rcp_f32_e32 v135, v134
	s_nop 0
	v_fma_f32 v136, -v134, v135, 1.0
	v_fmac_f32_e32 v135, v136, v135
	v_div_scale_f32 v136, vcc, v80, v133, v80
	v_mul_f32_e32 v137, v136, v135
	v_fma_f32 v138, -v134, v137, v136
	v_fmac_f32_e32 v137, v138, v135
	v_fma_f32 v134, -v134, v137, v136
	v_div_fmas_f32 v134, v134, v135, v137
	v_div_fixup_f32 v80, v134, v133, v80
	v_add_u32_e32 v134, 0x80, v132
	v_ashrrev_i32_e32 v135, 31, v134
	v_lshl_add_u64 v[134:135], v[134:135], 2, s[90:91]
	v_add_co_u32_e32 v136, vcc, s18, v134
	v_pk_mul_f32 v[78:79], v[80:81], v[78:79] op_sel_hi:[0,1]
	s_nop 0
	v_addc_co_u32_e32 v137, vcc, 0, v135, vcc
	v_add_co_u32_e32 v134, vcc, s31, v134
	s_nop 0
	s_nop 0
	v_addc_co_u32_e32 v135, vcc, 0, v135, vcc
	s_nop 0
	v_pk_mul_f32 v[76:77], v[80:81], v[76:77] op_sel_hi:[0,1]
	v_pk_mul_f32 v[74:75], v[80:81], v[74:75] op_sel_hi:[0,1]
	v_pk_mul_f32 v[72:73], v[80:81], v[72:73] op_sel_hi:[0,1]
	v_pk_mul_f32 v[70:71], v[80:81], v[70:71] op_sel_hi:[0,1]
	v_pk_mul_f32 v[68:69], v[80:81], v[68:69] op_sel_hi:[0,1]
	v_pk_mul_f32 v[66:67], v[80:81], v[66:67] op_sel_hi:[0,1]
	v_pk_mul_f32 v[64:65], v[80:81], v[64:65] op_sel_hi:[0,1]
	s_waitcnt vmcnt(6)
	v_pk_fma_f32 v[134:135], v[212:213], s[70:71], v[82:83] op_sel_hi:[1,0,0]
	s_nop 0
	v_mul_f32_e32 v80, 0x4b800000, v134
	v_cmp_gt_f32_e64 s[40:41], s19, v134
	v_cmp_gt_f32_e32 vcc, s19, v135
	s_nop 0
	v_cndmask_b32_e64 v80, v134, v80, s[40:41]
	v_rsq_f32_e32 v134, v80
	v_mul_f32_e32 v80, 0x4b800000, v135
	v_cndmask_b32_e32 v80, v135, v80, vcc
	v_rsq_f32_e32 v135, v80
	s_nop 0
	v_pk_mul_f32 v[136:137], v[134:135], s[8:9] op_sel_hi:[1,0]
	s_nop 0
	v_cndmask_b32_e64 v80, v134, v136, s[40:41]
	v_cndmask_b32_e32 v133, v135, v137, vcc
	v_div_scale_f32 v134, s[36:37], v133, v133, v80
	v_rcp_f32_e32 v135, v134
	s_nop 0
	v_fma_f32 v136, -v134, v135, 1.0
	v_fmac_f32_e32 v135, v136, v135
	v_div_scale_f32 v136, vcc, v80, v133, v80
	v_mul_f32_e32 v137, v136, v135
	v_fma_f32 v138, -v134, v137, v136
	v_fmac_f32_e32 v137, v138, v135
	v_fma_f32 v134, -v134, v137, v136
	v_div_fmas_f32 v134, v134, v135, v137
	v_div_fixup_f32 v80, v134, v133, v80
	v_add_u32_e32 v134, 0x90, v132
	v_ashrrev_i32_e32 v135, 31, v134
	v_lshl_add_u64 v[134:135], v[134:135], 2, s[90:91]
	v_add_co_u32_e32 v136, vcc, s18, v134
	v_pk_mul_f32 v[62:63], v[80:81], v[62:63] op_sel_hi:[0,1]
	s_nop 0
	v_addc_co_u32_e32 v137, vcc, 0, v135, vcc
	v_add_co_u32_e32 v134, vcc, s31, v134
	s_nop 0
	s_nop 0
	v_addc_co_u32_e32 v135, vcc, 0, v135, vcc
	s_nop 0
	v_pk_mul_f32 v[60:61], v[80:81], v[60:61] op_sel_hi:[0,1]
	v_pk_mul_f32 v[58:59], v[80:81], v[58:59] op_sel_hi:[0,1]
	v_pk_mul_f32 v[56:57], v[80:81], v[56:57] op_sel_hi:[0,1]
	v_pk_mul_f32 v[54:55], v[80:81], v[54:55] op_sel_hi:[0,1]
	v_pk_mul_f32 v[52:53], v[80:81], v[52:53] op_sel_hi:[0,1]
	v_pk_mul_f32 v[50:51], v[80:81], v[50:51] op_sel_hi:[0,1]
	v_pk_mul_f32 v[48:49], v[80:81], v[48:49] op_sel_hi:[0,1]
	s_waitcnt vmcnt(4)
	v_pk_fma_f32 v[134:135], v[214:215], s[70:71], v[82:83] op_sel_hi:[1,0,0]
	s_nop 0
	v_mul_f32_e32 v80, 0x4b800000, v134
	v_cmp_gt_f32_e64 s[40:41], s19, v134
	v_cmp_gt_f32_e32 vcc, s19, v135
	s_nop 0
	v_cndmask_b32_e64 v80, v134, v80, s[40:41]
	v_rsq_f32_e32 v134, v80
	v_mul_f32_e32 v80, 0x4b800000, v135
	v_cndmask_b32_e32 v80, v135, v80, vcc
	v_rsq_f32_e32 v135, v80
	s_nop 0
	v_pk_mul_f32 v[136:137], v[134:135], s[8:9] op_sel_hi:[1,0]
	s_nop 0
	v_cndmask_b32_e64 v80, v134, v136, s[40:41]
	v_cndmask_b32_e32 v133, v135, v137, vcc
	v_div_scale_f32 v134, s[36:37], v133, v133, v80
	v_rcp_f32_e32 v135, v134
	s_nop 0
	v_fma_f32 v136, -v134, v135, 1.0
	v_fmac_f32_e32 v135, v136, v135
	v_div_scale_f32 v136, vcc, v80, v133, v80
	v_mul_f32_e32 v137, v136, v135
	v_fma_f32 v138, -v134, v137, v136
	v_fmac_f32_e32 v137, v138, v135
	v_fma_f32 v134, -v134, v137, v136
	v_div_fmas_f32 v134, v134, v135, v137
	v_div_fixup_f32 v80, v134, v133, v80
	v_add_u32_e32 v134, 0xa0, v132
	v_ashrrev_i32_e32 v135, 31, v134
	v_lshl_add_u64 v[134:135], v[134:135], 2, s[90:91]
	v_add_co_u32_e32 v136, vcc, s18, v134
	v_pk_mul_f32 v[46:47], v[80:81], v[46:47] op_sel_hi:[0,1]
	s_nop 0
	v_addc_co_u32_e32 v137, vcc, 0, v135, vcc
	v_add_co_u32_e32 v134, vcc, s31, v134
	s_nop 0
	s_nop 0
	v_addc_co_u32_e32 v135, vcc, 0, v135, vcc
	s_nop 0
	v_pk_mul_f32 v[44:45], v[80:81], v[44:45] op_sel_hi:[0,1]
	v_pk_mul_f32 v[42:43], v[80:81], v[42:43] op_sel_hi:[0,1]
	v_pk_mul_f32 v[40:41], v[80:81], v[40:41] op_sel_hi:[0,1]
	v_pk_mul_f32 v[38:39], v[80:81], v[38:39] op_sel_hi:[0,1]
	v_pk_mul_f32 v[36:37], v[80:81], v[36:37] op_sel_hi:[0,1]
	v_pk_mul_f32 v[34:35], v[80:81], v[34:35] op_sel_hi:[0,1]
	v_pk_mul_f32 v[32:33], v[80:81], v[32:33] op_sel_hi:[0,1]
	v_add_u32_e32 v132, 0xb0, v132
	s_waitcnt vmcnt(2)
	v_pk_fma_f32 v[134:135], v[216:217], s[70:71], v[82:83] op_sel_hi:[1,0,0]
	s_nop 0
	v_mul_f32_e32 v80, 0x4b800000, v134
	v_cmp_gt_f32_e64 s[40:41], s19, v134
	v_cmp_gt_f32_e32 vcc, s19, v135
	s_nop 0
	v_cndmask_b32_e64 v80, v134, v80, s[40:41]
	v_rsq_f32_e32 v134, v80
	v_mul_f32_e32 v80, 0x4b800000, v135
	v_cndmask_b32_e32 v80, v135, v80, vcc
	v_rsq_f32_e32 v135, v80
	s_nop 0
	v_pk_mul_f32 v[136:137], v[134:135], s[8:9] op_sel_hi:[1,0]
	s_nop 0
	v_cndmask_b32_e64 v80, v134, v136, s[40:41]
	v_cndmask_b32_e32 v133, v135, v137, vcc
	v_div_scale_f32 v134, s[36:37], v133, v133, v80
	v_rcp_f32_e32 v135, v134
	s_nop 0
	v_fma_f32 v136, -v134, v135, 1.0
	v_fmac_f32_e32 v135, v136, v135
	v_div_scale_f32 v136, vcc, v80, v133, v80
	v_mul_f32_e32 v137, v136, v135
	v_fma_f32 v138, -v134, v137, v136
	v_fmac_f32_e32 v137, v138, v135
	v_fma_f32 v134, -v134, v137, v136
	v_div_fmas_f32 v134, v134, v135, v137
	v_div_fixup_f32 v80, v134, v133, v80
	v_ashrrev_i32_e32 v133, 31, v132
	v_lshl_add_u64 v[134:135], v[132:133], 2, s[90:91]
	v_add_co_u32_e32 v132, vcc, s18, v134
	v_pk_mul_f32 v[30:31], v[80:81], v[30:31] op_sel_hi:[0,1]
	s_nop 0
	v_addc_co_u32_e32 v133, vcc, 0, v135, vcc
	v_add_co_u32_e32 v134, vcc, s31, v134
	s_nop 0
	s_nop 0
	v_addc_co_u32_e32 v135, vcc, 0, v135, vcc
	s_nop 0
	v_pk_mul_f32 v[28:29], v[80:81], v[28:29] op_sel_hi:[0,1]
	v_pk_mul_f32 v[26:27], v[80:81], v[26:27] op_sel_hi:[0,1]
	v_pk_mul_f32 v[24:25], v[80:81], v[24:25] op_sel_hi:[0,1]
	v_pk_mul_f32 v[22:23], v[80:81], v[22:23] op_sel_hi:[0,1]
	v_pk_mul_f32 v[20:21], v[80:81], v[20:21] op_sel_hi:[0,1]
	v_pk_mul_f32 v[18:19], v[80:81], v[18:19] op_sel_hi:[0,1]
	v_pk_mul_f32 v[16:17], v[80:81], v[16:17] op_sel_hi:[0,1]
	s_waitcnt vmcnt(0)
	v_pk_fma_f32 v[82:83], v[218:219], s[70:71], v[82:83] op_sel_hi:[1,0,0]
	s_nop 0
	v_mul_f32_e32 v80, 0x4b800000, v82
	v_cmp_gt_f32_e64 s[40:41], s19, v82
	v_cmp_gt_f32_e32 vcc, s19, v83
	s_nop 0
	v_cndmask_b32_e64 v80, v82, v80, s[40:41]
	v_rsq_f32_e32 v82, v80
	v_mul_f32_e32 v80, 0x4b800000, v83
	v_cndmask_b32_e32 v80, v83, v80, vcc
	v_rsq_f32_e32 v83, v80
	s_nop 0
	v_pk_mul_f32 v[132:133], v[82:83], s[8:9] op_sel_hi:[1,0]
	s_nop 0
	v_cndmask_b32_e64 v80, v82, v132, s[40:41]
	v_cndmask_b32_e32 v82, v83, v133, vcc
	v_div_scale_f32 v83, s[36:37], v82, v82, v80
	v_rcp_f32_e32 v132, v83
	s_mov_b32 s40, s96
	v_fma_f32 v133, -v83, v132, 1.0
	v_fmac_f32_e32 v132, v133, v132
	v_div_scale_f32 v133, vcc, v80, v82, v80
	v_mul_f32_e32 v134, v133, v132
	v_fma_f32 v135, -v83, v134, v133
	v_fmac_f32_e32 v134, v135, v132
	v_fma_f32 v83, -v83, v134, v133
	v_div_fmas_f32 v83, v83, v132, v134
	v_div_fixup_f32 v80, v83, v82, v80
	v_pk_mul_f32 v[14:15], v[80:81], v[14:15] op_sel_hi:[0,1]
	v_pk_mul_f32 v[12:13], v[80:81], v[12:13] op_sel_hi:[0,1]
	v_pk_mul_f32 v[10:11], v[80:81], v[10:11] op_sel_hi:[0,1]
	v_pk_mul_f32 v[8:9], v[80:81], v[8:9] op_sel_hi:[0,1]
	v_pk_mul_f32 v[6:7], v[80:81], v[6:7] op_sel_hi:[0,1]
	v_pk_mul_f32 v[4:5], v[80:81], v[4:5] op_sel_hi:[0,1]
	v_pk_mul_f32 v[2:3], v[80:81], v[2:3] op_sel_hi:[0,1]
	v_pk_mul_f32 v[0:1], v[80:81], v[0:1] op_sel_hi:[0,1]
	s_branch .LBB0_856
